# layer-1 FFN-in SwiGLU epilogues regenerated with packed f32 ops for the -log2e multiply and the +1 (same per-element operations), on the tail-split base
# speedup vs baseline: 1.0015x; 1.0015x over previous
.LBB0_1566:
	s_lshl_b32 s9, s18, 7
	s_or_b32 s9, s9, s39
	s_mul_i32 s11, s16, 44
	s_ashr_i32 s9, s9, 6
	s_add_i32 s20, s9, s11
	s_ashr_i32 s21, s20, 31
	s_lshl_b64 s[20:21], s[20:21], 15
	s_cmp_eq_u32 s54, 2
	s_cselect_b32 s55, 0x4000, 0
	s_add_u32 s20, s20, s55
	s_addc_u32 s21, s21, 0
	s_andn2_b64 vcc, exec, s[0:1]
	s_mov_b64 s[0:1], -1
	s_mov_b32 s56, 0xbfb8aa3b
	s_mov_b32 s57, s56
	v_lshl_add_u64 v[162:163], v[136:137], 0, s[20:21]
	v_pk_mul_f32 v[168:169], v[124:125], s[56:57] op_sel_hi:[1,0]
	v_pk_mul_f32 v[170:171], v[126:127], s[56:57] op_sel_hi:[1,0]
	v_pk_mul_f32 v[172:173], v[116:117], s[56:57] op_sel_hi:[1,0]
	v_pk_mul_f32 v[174:175], v[118:119], s[56:57] op_sel_hi:[1,0]
	v_exp_f32_e32 v168, v168
	v_exp_f32_e32 v169, v169
	v_exp_f32_e32 v170, v170
	v_exp_f32_e32 v171, v171
	v_exp_f32_e32 v172, v172
	v_exp_f32_e32 v173, v173
	v_exp_f32_e32 v174, v174
	v_exp_f32_e32 v175, v175
	v_pk_add_f32 v[168:169], v[168:169], 1.0 op_sel_hi:[1,0]
	v_pk_add_f32 v[170:171], v[170:171], 1.0 op_sel_hi:[1,0]
	v_pk_add_f32 v[172:173], v[172:173], 1.0 op_sel_hi:[1,0]
	v_pk_add_f32 v[174:175], v[174:175], 1.0 op_sel_hi:[1,0]
	v_rcp_f32_e32 v168, v168
	v_rcp_f32_e32 v169, v169
	v_rcp_f32_e32 v170, v170
	v_rcp_f32_e32 v171, v171
	v_rcp_f32_e32 v172, v172
	v_rcp_f32_e32 v173, v173
	v_rcp_f32_e32 v174, v174
	v_rcp_f32_e32 v175, v175
	v_pk_mul_f32 v[124:125], v[124:125], v[168:169]
	v_pk_mul_f32 v[126:127], v[126:127], v[170:171]
	v_pk_mul_f32 v[116:117], v[116:117], v[172:173]
	v_pk_mul_f32 v[118:119], v[118:119], v[174:175]
	v_pk_mul_f32 v[120:121], v[124:125], v[120:121]
	v_pk_mul_f32 v[122:123], v[126:127], v[122:123]
	v_pk_mul_f32 v[112:113], v[116:117], v[112:113]
	v_pk_mul_f32 v[114:115], v[118:119], v[114:115]
	v_cvt_pk_bf16_f32 v120, v120, v121
	v_cvt_pk_bf16_f32 v121, v122, v123
	v_cvt_pk_bf16_f32 v122, v112, v113
	v_cvt_pk_bf16_f32 v123, v114, v115
	v_lshl_add_u64 v[176:177], v[162:163], 0, v[138:139]
	global_store_dwordx4 v[176:177], v[120:123], off
	v_pk_mul_f32 v[168:169], v[108:109], s[56:57] op_sel_hi:[1,0]
	v_pk_mul_f32 v[170:171], v[110:111], s[56:57] op_sel_hi:[1,0]
	v_pk_mul_f32 v[172:173], v[100:101], s[56:57] op_sel_hi:[1,0]
	v_pk_mul_f32 v[174:175], v[102:103], s[56:57] op_sel_hi:[1,0]
	v_exp_f32_e32 v168, v168
	v_exp_f32_e32 v169, v169
	v_exp_f32_e32 v170, v170
	v_exp_f32_e32 v171, v171
	v_exp_f32_e32 v172, v172
	v_exp_f32_e32 v173, v173
	v_exp_f32_e32 v174, v174
	v_exp_f32_e32 v175, v175
	v_pk_add_f32 v[168:169], v[168:169], 1.0 op_sel_hi:[1,0]
	v_pk_add_f32 v[170:171], v[170:171], 1.0 op_sel_hi:[1,0]
	v_pk_add_f32 v[172:173], v[172:173], 1.0 op_sel_hi:[1,0]
	v_pk_add_f32 v[174:175], v[174:175], 1.0 op_sel_hi:[1,0]
	v_rcp_f32_e32 v168, v168
	v_rcp_f32_e32 v169, v169
	v_rcp_f32_e32 v170, v170
	v_rcp_f32_e32 v171, v171
	v_rcp_f32_e32 v172, v172
	v_rcp_f32_e32 v173, v173
	v_rcp_f32_e32 v174, v174
	v_rcp_f32_e32 v175, v175
	v_pk_mul_f32 v[108:109], v[108:109], v[168:169]
	v_pk_mul_f32 v[110:111], v[110:111], v[170:171]
	v_pk_mul_f32 v[100:101], v[100:101], v[172:173]
	v_pk_mul_f32 v[102:103], v[102:103], v[174:175]
	v_pk_mul_f32 v[104:105], v[108:109], v[104:105]
	v_pk_mul_f32 v[106:107], v[110:111], v[106:107]
	v_pk_mul_f32 v[96:97], v[100:101], v[96:97]
	v_pk_mul_f32 v[98:99], v[102:103], v[98:99]
	v_cvt_pk_bf16_f32 v104, v104, v105
	v_cvt_pk_bf16_f32 v105, v106, v107
	v_cvt_pk_bf16_f32 v106, v96, v97
	v_cvt_pk_bf16_f32 v107, v98, v99
	v_lshl_add_u64 v[176:177], v[162:163], 0, v[140:141]
	global_store_dwordx4 v[176:177], v[104:107], off
	v_pk_mul_f32 v[168:169], v[92:93], s[56:57] op_sel_hi:[1,0]
	v_pk_mul_f32 v[170:171], v[94:95], s[56:57] op_sel_hi:[1,0]
	v_pk_mul_f32 v[172:173], v[84:85], s[56:57] op_sel_hi:[1,0]
	v_pk_mul_f32 v[174:175], v[86:87], s[56:57] op_sel_hi:[1,0]
	v_exp_f32_e32 v168, v168
	v_exp_f32_e32 v169, v169
	v_exp_f32_e32 v170, v170
	v_exp_f32_e32 v171, v171
	v_exp_f32_e32 v172, v172
	v_exp_f32_e32 v173, v173
	v_exp_f32_e32 v174, v174
	v_exp_f32_e32 v175, v175
	v_pk_add_f32 v[168:169], v[168:169], 1.0 op_sel_hi:[1,0]
	v_pk_add_f32 v[170:171], v[170:171], 1.0 op_sel_hi:[1,0]
	v_pk_add_f32 v[172:173], v[172:173], 1.0 op_sel_hi:[1,0]
	v_pk_add_f32 v[174:175], v[174:175], 1.0 op_sel_hi:[1,0]
	v_rcp_f32_e32 v168, v168
	v_rcp_f32_e32 v169, v169
	v_rcp_f32_e32 v170, v170
	v_rcp_f32_e32 v171, v171
	v_rcp_f32_e32 v172, v172
	v_rcp_f32_e32 v173, v173
	v_rcp_f32_e32 v174, v174
	v_rcp_f32_e32 v175, v175
	v_pk_mul_f32 v[92:93], v[92:93], v[168:169]
	v_pk_mul_f32 v[94:95], v[94:95], v[170:171]
	v_pk_mul_f32 v[84:85], v[84:85], v[172:173]
	v_pk_mul_f32 v[86:87], v[86:87], v[174:175]
	v_pk_mul_f32 v[88:89], v[92:93], v[88:89]
	v_pk_mul_f32 v[90:91], v[94:95], v[90:91]
	v_pk_mul_f32 v[80:81], v[84:85], v[80:81]
	v_pk_mul_f32 v[82:83], v[86:87], v[82:83]
	v_cvt_pk_bf16_f32 v88, v88, v89
	v_cvt_pk_bf16_f32 v89, v90, v91
	v_cvt_pk_bf16_f32 v90, v80, v81
	v_cvt_pk_bf16_f32 v91, v82, v83
	v_lshl_add_u64 v[176:177], v[162:163], 0, v[142:143]
	global_store_dwordx4 v[176:177], v[88:91], off
	v_pk_mul_f32 v[168:169], v[76:77], s[56:57] op_sel_hi:[1,0]
	v_pk_mul_f32 v[170:171], v[78:79], s[56:57] op_sel_hi:[1,0]
	v_pk_mul_f32 v[172:173], v[68:69], s[56:57] op_sel_hi:[1,0]
	v_pk_mul_f32 v[174:175], v[70:71], s[56:57] op_sel_hi:[1,0]
	v_exp_f32_e32 v168, v168
	v_exp_f32_e32 v169, v169
	v_exp_f32_e32 v170, v170
	v_exp_f32_e32 v171, v171
	v_exp_f32_e32 v172, v172
	v_exp_f32_e32 v173, v173
	v_exp_f32_e32 v174, v174
	v_exp_f32_e32 v175, v175
	v_pk_add_f32 v[168:169], v[168:169], 1.0 op_sel_hi:[1,0]
	v_pk_add_f32 v[170:171], v[170:171], 1.0 op_sel_hi:[1,0]
	v_pk_add_f32 v[172:173], v[172:173], 1.0 op_sel_hi:[1,0]
	v_pk_add_f32 v[174:175], v[174:175], 1.0 op_sel_hi:[1,0]
	v_rcp_f32_e32 v168, v168
	v_rcp_f32_e32 v169, v169
	v_rcp_f32_e32 v170, v170
	v_rcp_f32_e32 v171, v171
	v_rcp_f32_e32 v172, v172
	v_rcp_f32_e32 v173, v173
	v_rcp_f32_e32 v174, v174
	v_rcp_f32_e32 v175, v175
	v_pk_mul_f32 v[76:77], v[76:77], v[168:169]
	v_pk_mul_f32 v[78:79], v[78:79], v[170:171]
	v_pk_mul_f32 v[68:69], v[68:69], v[172:173]
	v_pk_mul_f32 v[70:71], v[70:71], v[174:175]
	v_pk_mul_f32 v[72:73], v[76:77], v[72:73]
	v_pk_mul_f32 v[74:75], v[78:79], v[74:75]
	v_pk_mul_f32 v[64:65], v[68:69], v[64:65]
	v_pk_mul_f32 v[66:67], v[70:71], v[66:67]
	v_cvt_pk_bf16_f32 v72, v72, v73
	v_cvt_pk_bf16_f32 v73, v74, v75
	v_cvt_pk_bf16_f32 v74, v64, v65
	v_cvt_pk_bf16_f32 v75, v66, v67
	v_lshl_add_u64 v[176:177], v[162:163], 0, v[144:145]
	global_store_dwordx4 v[176:177], v[72:75], off
	s_cmp_lg_u32 s54, 0
	s_cbranch_scc1 .Lts0_epi_end
	v_pk_mul_f32 v[168:169], v[60:61], s[56:57] op_sel_hi:[1,0]
	v_pk_mul_f32 v[170:171], v[62:63], s[56:57] op_sel_hi:[1,0]
	v_pk_mul_f32 v[172:173], v[52:53], s[56:57] op_sel_hi:[1,0]
	v_pk_mul_f32 v[174:175], v[54:55], s[56:57] op_sel_hi:[1,0]
	v_exp_f32_e32 v168, v168
	v_exp_f32_e32 v169, v169
	v_exp_f32_e32 v170, v170
	v_exp_f32_e32 v171, v171
	v_exp_f32_e32 v172, v172
	v_exp_f32_e32 v173, v173
	v_exp_f32_e32 v174, v174
	v_exp_f32_e32 v175, v175
	v_pk_add_f32 v[168:169], v[168:169], 1.0 op_sel_hi:[1,0]
	v_pk_add_f32 v[170:171], v[170:171], 1.0 op_sel_hi:[1,0]
	v_pk_add_f32 v[172:173], v[172:173], 1.0 op_sel_hi:[1,0]
	v_pk_add_f32 v[174:175], v[174:175], 1.0 op_sel_hi:[1,0]
	v_rcp_f32_e32 v168, v168
	v_rcp_f32_e32 v169, v169
	v_rcp_f32_e32 v170, v170
	v_rcp_f32_e32 v171, v171
	v_rcp_f32_e32 v172, v172
	v_rcp_f32_e32 v173, v173
	v_rcp_f32_e32 v174, v174
	v_rcp_f32_e32 v175, v175
	v_pk_mul_f32 v[60:61], v[60:61], v[168:169]
	v_pk_mul_f32 v[62:63], v[62:63], v[170:171]
	v_pk_mul_f32 v[52:53], v[52:53], v[172:173]
	v_pk_mul_f32 v[54:55], v[54:55], v[174:175]
	v_pk_mul_f32 v[56:57], v[60:61], v[56:57]
	v_pk_mul_f32 v[58:59], v[62:63], v[58:59]
	v_pk_mul_f32 v[48:49], v[52:53], v[48:49]
	v_pk_mul_f32 v[50:51], v[54:55], v[50:51]
	v_cvt_pk_bf16_f32 v56, v56, v57
	v_cvt_pk_bf16_f32 v57, v58, v59
	v_cvt_pk_bf16_f32 v58, v48, v49
	v_cvt_pk_bf16_f32 v59, v50, v51
	v_lshl_add_u64 v[176:177], v[162:163], 0, v[146:147]
	global_store_dwordx4 v[176:177], v[56:59], off
	v_pk_mul_f32 v[168:169], v[44:45], s[56:57] op_sel_hi:[1,0]
	v_pk_mul_f32 v[170:171], v[46:47], s[56:57] op_sel_hi:[1,0]
	v_pk_mul_f32 v[172:173], v[36:37], s[56:57] op_sel_hi:[1,0]
	v_pk_mul_f32 v[174:175], v[38:39], s[56:57] op_sel_hi:[1,0]
	v_exp_f32_e32 v168, v168
	v_exp_f32_e32 v169, v169
	v_exp_f32_e32 v170, v170
	v_exp_f32_e32 v171, v171
	v_exp_f32_e32 v172, v172
	v_exp_f32_e32 v173, v173
	v_exp_f32_e32 v174, v174
	v_exp_f32_e32 v175, v175
	v_pk_add_f32 v[168:169], v[168:169], 1.0 op_sel_hi:[1,0]
	v_pk_add_f32 v[170:171], v[170:171], 1.0 op_sel_hi:[1,0]
	v_pk_add_f32 v[172:173], v[172:173], 1.0 op_sel_hi:[1,0]
	v_pk_add_f32 v[174:175], v[174:175], 1.0 op_sel_hi:[1,0]
	v_rcp_f32_e32 v168, v168
	v_rcp_f32_e32 v169, v169
	v_rcp_f32_e32 v170, v170
	v_rcp_f32_e32 v171, v171
	v_rcp_f32_e32 v172, v172
	v_rcp_f32_e32 v173, v173
	v_rcp_f32_e32 v174, v174
	v_rcp_f32_e32 v175, v175
	v_pk_mul_f32 v[44:45], v[44:45], v[168:169]
	v_pk_mul_f32 v[46:47], v[46:47], v[170:171]
	v_pk_mul_f32 v[36:37], v[36:37], v[172:173]
	v_pk_mul_f32 v[38:39], v[38:39], v[174:175]
	v_pk_mul_f32 v[40:41], v[44:45], v[40:41]
	v_pk_mul_f32 v[42:43], v[46:47], v[42:43]
	v_pk_mul_f32 v[32:33], v[36:37], v[32:33]
	v_pk_mul_f32 v[34:35], v[38:39], v[34:35]
	v_cvt_pk_bf16_f32 v40, v40, v41
	v_cvt_pk_bf16_f32 v41, v42, v43
	v_cvt_pk_bf16_f32 v42, v32, v33
	v_cvt_pk_bf16_f32 v43, v34, v35
	v_lshl_add_u64 v[176:177], v[162:163], 0, v[148:149]
	global_store_dwordx4 v[176:177], v[40:43], off
	v_pk_mul_f32 v[168:169], v[28:29], s[56:57] op_sel_hi:[1,0]
	v_pk_mul_f32 v[170:171], v[30:31], s[56:57] op_sel_hi:[1,0]
	v_pk_mul_f32 v[172:173], v[20:21], s[56:57] op_sel_hi:[1,0]
	v_pk_mul_f32 v[174:175], v[22:23], s[56:57] op_sel_hi:[1,0]
	v_exp_f32_e32 v168, v168
	v_exp_f32_e32 v169, v169
	v_exp_f32_e32 v170, v170
	v_exp_f32_e32 v171, v171
	v_exp_f32_e32 v172, v172
	v_exp_f32_e32 v173, v173
	v_exp_f32_e32 v174, v174
	v_exp_f32_e32 v175, v175
	v_pk_add_f32 v[168:169], v[168:169], 1.0 op_sel_hi:[1,0]
	v_pk_add_f32 v[170:171], v[170:171], 1.0 op_sel_hi:[1,0]
	v_pk_add_f32 v[172:173], v[172:173], 1.0 op_sel_hi:[1,0]
	v_pk_add_f32 v[174:175], v[174:175], 1.0 op_sel_hi:[1,0]
	v_rcp_f32_e32 v168, v168
	v_rcp_f32_e32 v169, v169
	v_rcp_f32_e32 v170, v170
	v_rcp_f32_e32 v171, v171
	v_rcp_f32_e32 v172, v172
	v_rcp_f32_e32 v173, v173
	v_rcp_f32_e32 v174, v174
	v_rcp_f32_e32 v175, v175
	v_pk_mul_f32 v[28:29], v[28:29], v[168:169]
	v_pk_mul_f32 v[30:31], v[30:31], v[170:171]
	v_pk_mul_f32 v[20:21], v[20:21], v[172:173]
	v_pk_mul_f32 v[22:23], v[22:23], v[174:175]
	v_pk_mul_f32 v[24:25], v[28:29], v[24:25]
	v_pk_mul_f32 v[26:27], v[30:31], v[26:27]
	v_pk_mul_f32 v[16:17], v[20:21], v[16:17]
	v_pk_mul_f32 v[18:19], v[22:23], v[18:19]
	v_cvt_pk_bf16_f32 v24, v24, v25
	v_cvt_pk_bf16_f32 v25, v26, v27
	v_cvt_pk_bf16_f32 v26, v16, v17
	v_cvt_pk_bf16_f32 v27, v18, v19
	v_lshl_add_u64 v[176:177], v[162:163], 0, v[150:151]
	global_store_dwordx4 v[176:177], v[24:27], off
	v_pk_mul_f32 v[168:169], v[12:13], s[56:57] op_sel_hi:[1,0]
	v_pk_mul_f32 v[170:171], v[14:15], s[56:57] op_sel_hi:[1,0]
	v_pk_mul_f32 v[172:173], v[4:5], s[56:57] op_sel_hi:[1,0]
	v_pk_mul_f32 v[174:175], v[6:7], s[56:57] op_sel_hi:[1,0]
	v_exp_f32_e32 v168, v168
	v_exp_f32_e32 v169, v169
	v_exp_f32_e32 v170, v170
	v_exp_f32_e32 v171, v171
	v_exp_f32_e32 v172, v172
	v_exp_f32_e32 v173, v173
	v_exp_f32_e32 v174, v174
	v_exp_f32_e32 v175, v175
	v_pk_add_f32 v[168:169], v[168:169], 1.0 op_sel_hi:[1,0]
	v_pk_add_f32 v[170:171], v[170:171], 1.0 op_sel_hi:[1,0]
	v_pk_add_f32 v[172:173], v[172:173], 1.0 op_sel_hi:[1,0]
	v_pk_add_f32 v[174:175], v[174:175], 1.0 op_sel_hi:[1,0]
	v_rcp_f32_e32 v168, v168
	v_rcp_f32_e32 v169, v169
	v_rcp_f32_e32 v170, v170
	v_rcp_f32_e32 v171, v171
	v_rcp_f32_e32 v172, v172
	v_rcp_f32_e32 v173, v173
	v_rcp_f32_e32 v174, v174
	v_rcp_f32_e32 v175, v175
	v_pk_mul_f32 v[12:13], v[12:13], v[168:169]
	v_pk_mul_f32 v[14:15], v[14:15], v[170:171]
	v_pk_mul_f32 v[4:5], v[4:5], v[172:173]
	v_pk_mul_f32 v[6:7], v[6:7], v[174:175]
	v_pk_mul_f32 v[8:9], v[12:13], v[8:9]
	v_pk_mul_f32 v[10:11], v[14:15], v[10:11]
	v_pk_mul_f32 v[0:1], v[4:5], v[0:1]
	v_pk_mul_f32 v[2:3], v[6:7], v[2:3]
	v_cvt_pk_bf16_f32 v8, v8, v9
	v_cvt_pk_bf16_f32 v9, v10, v11
	v_cvt_pk_bf16_f32 v10, v0, v1
	v_cvt_pk_bf16_f32 v11, v2, v3
	v_lshl_add_u64 v[176:177], v[162:163], 0, v[152:153]
	global_store_dwordx4 v[176:177], v[8:11], off
